# grid barrier: XCD leaders wait on the cross-XCD arrival counter itself instead of the generation word bumped one atomic round trip later (plus early non-leader invalidate, P9/P10 epilogues)
# speedup vs baseline: 1.0242x; 1.0025x over previous
; __device__ __forceinline__ unsigned xb_ld(unsigned* p)              { return __hip_atomic_load(p, __ATOMIC_RELAXED, __HIP_MEMORY_SCOPE_AGENT); }
; __device__ __forceinline__ unsigned xb_add(unsigned* p, unsigned v) { return __hip_atomic_fetch_add(p, v, __ATOMIC_RELAXED, __HIP_MEMORY_SCOPE_AGENT); }
; #define XB_SPIN(cond, bar) do { unsigned _sp = 0; while (cond) { __builtin_amdgcn_s_sleep(1); \
;     if ((++_sp & 255u) == 0u) { if (xb_ld(&(bar)[XB_TMO])) break; if (_sp > XB_SPIN_CAP) { atomicAdd(&(bar)[XB_TMO], 1u); break; } } } } while (0)
; __device__ __forceinline__ void xcd_barrier(const XcdBarrier& b) {
;     ...
;             const unsigned og = xb_add(&bar[XB_TOP], 1u);
;             const unsigned tg = og / nx;
;             if (og + 1u == (tg + 1u) * nx) xb_add(&bar[XB_TOPGEN], 1u);
;             else XB_SPIN(xb_ld(&bar[XB_TOPGEN]) == tg, bar);
.LBB0_164:
	s_or_b64 exec, exec, s[6:7]
	s_waitcnt vmcnt(0)
	v_readfirstlane_b32 s4, v4
	v_cvt_f32_u32_e32 v4, v2
	v_sub_u32_e32 v5, 0, v2
	v_add_u32_e32 v3, s4, v3
	s_mov_b64 s[6:7], -1
	v_rcp_iflag_f32_e32 v4, v4
	s_nop 0
	v_mul_f32_e32 v4, 0x4f7ffffe, v4
	v_cvt_u32_f32_e32 v4, v4
	v_mul_lo_u32 v5, v5, v4
	v_mul_hi_u32 v5, v4, v5
	v_add_u32_e32 v4, v4, v5
	v_mul_hi_u32 v4, v3, v4
	v_mul_lo_u32 v5, v4, v2
	v_sub_u32_e32 v5, v3, v5
	v_cmp_ge_u32_e32 vcc, v5, v2
	v_add_u32_e32 v6, 1, v4
	v_add_u32_e32 v3, 1, v3
	v_cndmask_b32_e32 v4, v4, v6, vcc
	v_sub_u32_e32 v6, v5, v2
	v_cndmask_b32_e32 v5, v5, v6, vcc
	v_cmp_ge_u32_e32 vcc, v5, v2
	v_add_u32_e32 v5, 1, v4
	s_nop 0
	v_cndmask_b32_e32 v4, v4, v5, vcc
	v_mul_lo_u32 v5, v2, v4
	v_add_u32_e32 v2, v5, v2
	v_mov_b32_e32 v7, v2
	s_nop 0
	v_cmp_ne_u32_e32 vcc, v3, v2
	v_mov_b64_e32 v[2:3], s[74:75]
	s_and_saveexec_b64 s[4:5], vcc
	s_cbranch_execz .LBB0_176
	global_load_dword v2, v131, s[74:75] offset:-256 sc1
	s_mov_b64 s[36:37], 0
	s_waitcnt vmcnt(0)
	v_cmp_lt_u32_e32 vcc, v2, v7
	s_and_saveexec_b64 s[6:7], vcc
	s_cbranch_execz .LBB0_175
	s_mov_b64 s[50:51], s[42:43]
	s_mov_b32 s46, 1
	s_branch .LBB0_168

; __device__ __forceinline__ unsigned xb_ld(unsigned* p)              { return __hip_atomic_load(p, __ATOMIC_RELAXED, __HIP_MEMORY_SCOPE_AGENT); }
; __device__ __forceinline__ unsigned xb_add(unsigned* p, unsigned v) { return __hip_atomic_fetch_add(p, v, __ATOMIC_RELAXED, __HIP_MEMORY_SCOPE_AGENT); }
; #define XB_SPIN(cond, bar) do { unsigned _sp = 0; while (cond) { __builtin_amdgcn_s_sleep(1); \
;     if ((++_sp & 255u) == 0u) { if (xb_ld(&(bar)[XB_TMO])) break; if (_sp > XB_SPIN_CAP) { atomicAdd(&(bar)[XB_TMO], 1u); break; } } } } while (0)
; __device__ __forceinline__ void xcd_barrier(const XcdBarrier& b) {
;     ...
;             const unsigned og = xb_add(&bar[XB_TOP], 1u);
;             const unsigned tg = og / nx;
;             if (og + 1u == (tg + 1u) * nx) xb_add(&bar[XB_TOPGEN], 1u);
;             else XB_SPIN(xb_ld(&bar[XB_TOPGEN]) == tg, bar);
.LBB0_170:
	global_load_dword v2, v131, s[74:75] offset:-256 sc1
	s_add_i32 s46, s46, 1
	s_mov_b64 s[42:43], -1
	s_waitcnt vmcnt(0)
	v_cmp_ge_u32_e32 vcc, v2, v7
	s_orn2_b64 s[40:41], vcc, exec
	s_branch .LBB0_167

; __device__ __forceinline__ unsigned xb_ld(unsigned* p)              { return __hip_atomic_load(p, __ATOMIC_RELAXED, __HIP_MEMORY_SCOPE_AGENT); }
; __device__ __forceinline__ unsigned xb_add(unsigned* p, unsigned v) { return __hip_atomic_fetch_add(p, v, __ATOMIC_RELAXED, __HIP_MEMORY_SCOPE_AGENT); }
; #define XB_SPIN(cond, bar) do { unsigned _sp = 0; while (cond) { __builtin_amdgcn_s_sleep(1); \
;     if ((++_sp & 255u) == 0u) { if (xb_ld(&(bar)[XB_TMO])) break; if (_sp > XB_SPIN_CAP) { atomicAdd(&(bar)[XB_TMO], 1u); break; } } } } while (0)
; __device__ __forceinline__ void xcd_barrier(const XcdBarrier& b) {
;     ...
;             const unsigned og = xb_add(&bar[XB_TOP], 1u);
;             const unsigned tg = og / nx;
;             if (og + 1u == (tg + 1u) * nx) xb_add(&bar[XB_TOPGEN], 1u);
;             else XB_SPIN(xb_ld(&bar[XB_TOPGEN]) == tg, bar);
.LBB0_471:
	s_or_b64 exec, exec, s[6:7]
	s_waitcnt vmcnt(0)
	v_readfirstlane_b32 s4, v4
	v_cvt_f32_u32_e32 v4, v2
	v_sub_u32_e32 v5, 0, v2
	v_add_u32_e32 v3, s4, v3
	s_mov_b64 s[6:7], -1
	v_rcp_iflag_f32_e32 v4, v4
	s_nop 0
	v_mul_f32_e32 v4, 0x4f7ffffe, v4
	v_cvt_u32_f32_e32 v4, v4
	v_mul_lo_u32 v5, v5, v4
	v_mul_hi_u32 v5, v4, v5
	v_add_u32_e32 v4, v4, v5
	v_mul_hi_u32 v4, v3, v4
	v_mul_lo_u32 v5, v4, v2
	v_sub_u32_e32 v5, v3, v5
	v_cmp_ge_u32_e32 vcc, v5, v2
	v_add_u32_e32 v6, 1, v4
	v_add_u32_e32 v3, 1, v3
	v_cndmask_b32_e32 v4, v4, v6, vcc
	v_sub_u32_e32 v6, v5, v2
	v_cndmask_b32_e32 v5, v5, v6, vcc
	v_cmp_ge_u32_e32 vcc, v5, v2
	v_add_u32_e32 v5, 1, v4
	s_nop 0
	v_cndmask_b32_e32 v4, v4, v5, vcc
	v_mul_lo_u32 v5, v2, v4
	v_add_u32_e32 v2, v5, v2
	v_mov_b32_e32 v7, v2
	s_nop 0
	v_cmp_ne_u32_e32 vcc, v3, v2
	v_mov_b64_e32 v[2:3], s[74:75]
	s_and_saveexec_b64 s[4:5], vcc
	s_cbranch_execz .LBB0_483
	global_load_dword v2, v131, s[74:75] offset:-256 sc1
	s_mov_b64 s[36:37], 0
	s_waitcnt vmcnt(0)
	v_cmp_lt_u32_e32 vcc, v2, v7
	s_and_saveexec_b64 s[6:7], vcc
	s_cbranch_execz .LBB0_482
	s_mov_b32 s46, 1
	s_branch .LBB0_475

; __device__ __forceinline__ unsigned xb_ld(unsigned* p)              { return __hip_atomic_load(p, __ATOMIC_RELAXED, __HIP_MEMORY_SCOPE_AGENT); }
; __device__ __forceinline__ unsigned xb_add(unsigned* p, unsigned v) { return __hip_atomic_fetch_add(p, v, __ATOMIC_RELAXED, __HIP_MEMORY_SCOPE_AGENT); }
; #define XB_SPIN(cond, bar) do { unsigned _sp = 0; while (cond) { __builtin_amdgcn_s_sleep(1); \
;     if ((++_sp & 255u) == 0u) { if (xb_ld(&(bar)[XB_TMO])) break; if (_sp > XB_SPIN_CAP) { atomicAdd(&(bar)[XB_TMO], 1u); break; } } } } while (0)
; __device__ __forceinline__ void xcd_barrier(const XcdBarrier& b) {
;     ...
;             const unsigned og = xb_add(&bar[XB_TOP], 1u);
;             const unsigned tg = og / nx;
;             if (og + 1u == (tg + 1u) * nx) xb_add(&bar[XB_TOPGEN], 1u);
;             else XB_SPIN(xb_ld(&bar[XB_TOPGEN]) == tg, bar);
.LBB0_756:
	s_or_b64 exec, exec, s[6:7]
	s_waitcnt vmcnt(0)
	v_readfirstlane_b32 s4, v4
	v_cvt_f32_u32_e32 v4, v2
	v_sub_u32_e32 v5, 0, v2
	v_add_u32_e32 v3, s4, v3
	s_mov_b64 s[6:7], -1
	v_rcp_iflag_f32_e32 v4, v4
	s_nop 0
	v_mul_f32_e32 v4, 0x4f7ffffe, v4
	v_cvt_u32_f32_e32 v4, v4
	v_mul_lo_u32 v5, v5, v4
	v_mul_hi_u32 v5, v4, v5
	v_add_u32_e32 v4, v4, v5
	v_mul_hi_u32 v4, v3, v4
	v_mul_lo_u32 v5, v4, v2
	v_sub_u32_e32 v5, v3, v5
	v_cmp_ge_u32_e32 vcc, v5, v2
	v_add_u32_e32 v6, 1, v4
	v_add_u32_e32 v3, 1, v3
	v_cndmask_b32_e32 v4, v4, v6, vcc
	v_sub_u32_e32 v6, v5, v2
	v_cndmask_b32_e32 v5, v5, v6, vcc
	v_cmp_ge_u32_e32 vcc, v5, v2
	v_add_u32_e32 v5, 1, v4
	s_nop 0
	v_cndmask_b32_e32 v4, v4, v5, vcc
	v_mul_lo_u32 v5, v2, v4
	v_add_u32_e32 v2, v5, v2
	v_mov_b32_e32 v7, v2
	s_nop 0
	v_cmp_ne_u32_e32 vcc, v3, v2
	v_mov_b64_e32 v[2:3], s[74:75]
	s_and_saveexec_b64 s[4:5], vcc
	s_cbranch_execz .LBB0_768
	global_load_dword v2, v131, s[74:75] offset:-256 sc1
	s_mov_b64 s[36:37], 0
	s_waitcnt vmcnt(0)
	v_cmp_lt_u32_e32 vcc, v2, v7
	s_and_saveexec_b64 s[6:7], vcc
	s_cbranch_execz .LBB0_767
	s_mov_b32 s34, 1
	s_branch .LBB0_760

; __device__ __forceinline__ unsigned xb_ld(unsigned* p)              { return __hip_atomic_load(p, __ATOMIC_RELAXED, __HIP_MEMORY_SCOPE_AGENT); }
; __device__ __forceinline__ unsigned xb_add(unsigned* p, unsigned v) { return __hip_atomic_fetch_add(p, v, __ATOMIC_RELAXED, __HIP_MEMORY_SCOPE_AGENT); }
; #define XB_SPIN(cond, bar) do { unsigned _sp = 0; while (cond) { __builtin_amdgcn_s_sleep(1); \
;     if ((++_sp & 255u) == 0u) { if (xb_ld(&(bar)[XB_TMO])) break; if (_sp > XB_SPIN_CAP) { atomicAdd(&(bar)[XB_TMO], 1u); break; } } } } while (0)
; __device__ __forceinline__ void xcd_barrier(const XcdBarrier& b) {
;     ...
;             const unsigned og = xb_add(&bar[XB_TOP], 1u);
;             const unsigned tg = og / nx;
;             if (og + 1u == (tg + 1u) * nx) xb_add(&bar[XB_TOPGEN], 1u);
;             else XB_SPIN(xb_ld(&bar[XB_TOPGEN]) == tg, bar);
.LBB0_762:
	global_load_dword v2, v131, s[74:75] offset:-256 sc1
	s_add_i32 s34, s34, 1
	s_mov_b64 s[42:43], -1
	s_waitcnt vmcnt(0)
	v_cmp_ge_u32_e32 vcc, v2, v7
	s_orn2_b64 s[40:41], vcc, exec
	s_branch .LBB0_759

; __device__ __forceinline__ unsigned xb_ld(unsigned* p)              { return __hip_atomic_load(p, __ATOMIC_RELAXED, __HIP_MEMORY_SCOPE_AGENT); }
; __device__ __forceinline__ unsigned xb_add(unsigned* p, unsigned v) { return __hip_atomic_fetch_add(p, v, __ATOMIC_RELAXED, __HIP_MEMORY_SCOPE_AGENT); }
; #define XB_SPIN(cond, bar) do { unsigned _sp = 0; while (cond) { __builtin_amdgcn_s_sleep(1); \
;     if ((++_sp & 255u) == 0u) { if (xb_ld(&(bar)[XB_TMO])) break; if (_sp > XB_SPIN_CAP) { atomicAdd(&(bar)[XB_TMO], 1u); break; } } } } while (0)
; __device__ __forceinline__ void xcd_barrier(const XcdBarrier& b) {
;     ...
;             const unsigned og = xb_add(&bar[XB_TOP], 1u);
;             const unsigned tg = og / nx;
;             if (og + 1u == (tg + 1u) * nx) xb_add(&bar[XB_TOPGEN], 1u);
;             else XB_SPIN(xb_ld(&bar[XB_TOPGEN]) == tg, bar);
.LBB0_858:
	s_or_b64 exec, exec, s[6:7]
	v_cvt_f32_u32_e32 v5, v2
	s_waitcnt vmcnt(0)
	v_readfirstlane_b32 s4, v4
	s_mov_b64 s[6:7], -1
	v_rcp_iflag_f32_e32 v5, v5
	v_add_u32_e32 v3, s4, v3
	v_add_u32_e32 v6, 1, v3
	v_mul_f32_e32 v4, 0x4f7ffffe, v5
	v_cvt_u32_f32_e32 v4, v4
	v_sub_u32_e32 v5, 0, v2
	v_mul_lo_u32 v5, v5, v4
	v_mul_hi_u32 v5, v4, v5
	v_add_u32_e32 v4, v4, v5
	v_mul_hi_u32 v4, v3, v4
	v_mul_lo_u32 v5, v4, v2
	v_sub_u32_e32 v3, v3, v5
	v_add_u32_e32 v7, 1, v4
	v_cmp_ge_u32_e32 vcc, v3, v2
	v_sub_u32_e32 v5, v3, v2
	s_nop 0
	v_cndmask_b32_e32 v4, v4, v7, vcc
	v_cndmask_b32_e32 v3, v3, v5, vcc
	v_add_u32_e32 v5, 1, v4
	v_cmp_ge_u32_e32 vcc, v3, v2
	s_nop 1
	v_cndmask_b32_e32 v4, v4, v5, vcc
	v_mul_lo_u32 v3, v2, v4
	v_add_u32_e32 v2, v3, v2
	v_mov_b32_e32 v7, v2
	s_nop 0
	v_cmp_ne_u32_e32 vcc, v6, v2
	v_mov_b64_e32 v[2:3], s[74:75]
	s_and_saveexec_b64 s[4:5], vcc
	s_cbranch_execz .LBB0_870
	v_mov_b32_e32 v2, 0
	global_load_dword v3, v2, s[74:75] offset:-256 sc1
	s_mov_b64 s[8:9], 0
	s_waitcnt vmcnt(0)
	v_cmp_lt_u32_e32 vcc, v3, v7
	s_and_saveexec_b64 s[6:7], vcc
	s_cbranch_execz .LBB0_869
	s_mov_b32 s18, 1
	s_branch .LBB0_862

; __device__ __forceinline__ unsigned xb_ld(unsigned* p)              { return __hip_atomic_load(p, __ATOMIC_RELAXED, __HIP_MEMORY_SCOPE_AGENT); }
; __device__ __forceinline__ unsigned xb_add(unsigned* p, unsigned v) { return __hip_atomic_fetch_add(p, v, __ATOMIC_RELAXED, __HIP_MEMORY_SCOPE_AGENT); }
; #define XB_SPIN(cond, bar) do { unsigned _sp = 0; while (cond) { __builtin_amdgcn_s_sleep(1); \
;     if ((++_sp & 255u) == 0u) { if (xb_ld(&(bar)[XB_TMO])) break; if (_sp > XB_SPIN_CAP) { atomicAdd(&(bar)[XB_TMO], 1u); break; } } } } while (0)
; __device__ __forceinline__ void xcd_barrier(const XcdBarrier& b) {
;     ...
;             const unsigned og = xb_add(&bar[XB_TOP], 1u);
;             const unsigned tg = og / nx;
;             if (og + 1u == (tg + 1u) * nx) xb_add(&bar[XB_TOPGEN], 1u);
;             else XB_SPIN(xb_ld(&bar[XB_TOPGEN]) == tg, bar);
.LBB0_864:
	global_load_dword v3, v2, s[74:75] offset:-256 sc1
	s_add_i32 s18, s18, 1
	s_mov_b64 s[12:13], -1
	s_waitcnt vmcnt(0)
	v_cmp_ge_u32_e32 vcc, v3, v7
	s_orn2_b64 s[16:17], vcc, exec
	s_branch .LBB0_861
